# P2 epilogue: bias consumers read the prefetched registers directly (16 staging v_mov deleted per unit) and the vestigial s_waitcnt vmcnt(0) at the epilogue head (bias loads moved to unit start earlier
# speedup vs baseline: 1.0026x; 1.0026x over previous
.LBB0_205:
	s_add_i32 s5, s4, -8
	s_cmp_gt_i32 s4, 15
	s_cselect_b64 s[30:31], -1, 0
	s_lshl_b32 s19, s4, 8
	v_mov_b32_e32 v175, v145
	v_mov_b32_e32 v52, v147
	s_or_b32 s19, s19, s56
	s_cmp_gt_i32 s4, 5
	v_lshl_add_u32 v164, v52, 3, s19
	v_ashrrev_i32_e32 v165, 31, v164
	v_lshlrev_b32_e32 v248, 1, v164
	v_lshl_add_u64 v[60:61], v[164:165], 2, s[10:11]
	s_cselect_b64 s[28:29], -1, 0
	s_cmp_lt_u32 s5, 6
	s_cselect_b64 s[4:5], -1, 0
	s_or_b64 s[4:5], s[30:31], s[4:5]
	s_and_b64 s[30:31], s[28:29], s[4:5]
	v_cndmask_b32_e64 v166, 0, 1, s[30:31]
	v_cmp_ne_u32_e64 s[4:5], 1, v166
	s_andn2_b64 vcc, exec, s[30:31]
	v_pk_add_f32 v[166:167], v[142:143], v[234:235]
	v_pk_add_f32 v[168:169], v[140:141], v[232:233]
	v_pk_add_f32 v[140:141], v[138:139], v[238:239]
	v_pk_add_f32 v[142:143], v[136:137], v[236:237]
	s_cbranch_vccnz .LBB0_207
	v_mul_f32_e32 v137, 0xbfb8aa3b, v142
	v_mul_f32_e32 v138, 0xbfb8aa3b, v169
	v_exp_f32_e32 v137, v137
	v_exp_f32_e32 v139, v138
	v_mul_f32_e32 v177, 0xbfb8aa3b, v140
	v_mul_f32_e32 v178, 0xbfb8aa3b, v167
	v_add_f32_e32 v137, 1.0, v137
	v_mul_f32_e32 v136, 0xbfb8aa3b, v168
	v_rcp_f32_e32 v138, v137
	v_add_f32_e32 v137, 1.0, v139
	v_mul_f32_e32 v139, 0xbfb8aa3b, v143
	v_mul_f32_e32 v176, 0xbfb8aa3b, v166
	v_exp_f32_e32 v177, v177
	v_exp_f32_e32 v179, v178
	v_mul_f32_e32 v178, 0xbfb8aa3b, v141
	v_exp_f32_e32 v136, v136
	v_exp_f32_e32 v139, v139
	v_exp_f32_e32 v176, v176
	v_exp_f32_e32 v180, v178
	v_add_f32_e32 v177, 1.0, v177
	v_add_f32_e32 v136, 1.0, v136
	v_add_f32_e32 v139, 1.0, v139
	v_add_f32_e32 v176, 1.0, v176
	v_rcp_f32_e32 v178, v177
	v_add_f32_e32 v177, 1.0, v179
	v_add_f32_e32 v179, 1.0, v180
	v_rcp_f32_e32 v136, v136
	v_rcp_f32_e32 v137, v137
	v_rcp_f32_e32 v176, v176
	v_rcp_f32_e32 v177, v177
	v_rcp_f32_e32 v179, v179
	v_rcp_f32_e32 v139, v139
	v_pk_mul_f32 v[168:169], v[168:169], v[136:137]
	v_pk_mul_f32 v[166:167], v[166:167], v[176:177]
	v_pk_mul_f32 v[140:141], v[140:141], v[178:179]
	v_pk_mul_f32 v[142:143], v[142:143], v[138:139]
.LBB0_207:
	s_lshl_b32 s19, s26, 8
	s_add_i32 s19, s19, s51
	v_add_u32_e32 v175, s19, v175
	v_cndmask_b32_e64 v136, v174, 1.0, s[28:29]
	v_mad_u32_u24 v138, v175, s71, v248
	v_pk_mul_f32 v[166:167], v[136:137], v[166:167] op_sel_hi:[0,1]
	v_pk_mul_f32 v[168:169], v[136:137], v[168:169] op_sel_hi:[0,1]
	v_pk_mul_f32 v[176:177], v[136:137], v[140:141] op_sel_hi:[0,1]
	v_pk_mul_f32 v[142:143], v[136:137], v[142:143] op_sel_hi:[0,1]
	v_cvt_pk_bf16_f32 v140, v168, v169
	v_cvt_pk_bf16_f32 v141, v166, v167
	v_cvt_pk_bf16_f32 v142, v142, v143
	v_cvt_pk_bf16_f32 v143, v176, v177
	global_store_dwordx4 v138, v[140:143], s[8:9] nt
	v_pk_add_f32 v[134:135], v[134:135], v[246:247]
	v_pk_add_f32 v[132:133], v[132:133], v[244:245]
	v_pk_add_f32 v[130:131], v[130:131], v[242:243]
	s_and_b64 vcc, exec, s[4:5]
	v_pk_add_f32 v[140:141], v[128:129], v[240:241]
	s_cbranch_vccnz .LBB0_209
	v_mul_f32_e32 v143, 0xbfb8aa3b, v134
	v_mul_f32_e32 v129, 0xbfb8aa3b, v140
	v_exp_f32_e32 v143, v143
	v_mul_f32_e32 v166, 0xbfb8aa3b, v130
	v_mul_f32_e32 v137, 0xbfb8aa3b, v133
	v_exp_f32_e32 v129, v129
	v_exp_f32_e32 v167, v166
	v_exp_f32_e32 v137, v137
	v_add_f32_e32 v143, 1.0, v143
	v_add_f32_e32 v129, 1.0, v129
	v_rcp_f32_e32 v166, v143
	v_add_f32_e32 v143, 1.0, v167
	v_mul_f32_e32 v167, 0xbfb8aa3b, v135
	v_mul_f32_e32 v128, 0xbfb8aa3b, v132
	v_rcp_f32_e32 v142, v129
	v_add_f32_e32 v129, 1.0, v137
	v_mul_f32_e32 v137, 0xbfb8aa3b, v141
	v_exp_f32_e32 v167, v167
	v_mul_f32_e32 v168, 0xbfb8aa3b, v131
	v_exp_f32_e32 v128, v128
	v_exp_f32_e32 v137, v137
	v_exp_f32_e32 v169, v168
	v_rcp_f32_e32 v168, v143
	v_add_f32_e32 v143, 1.0, v167
	v_add_f32_e32 v128, 1.0, v128
	v_add_f32_e32 v137, 1.0, v137
	v_rcp_f32_e32 v167, v143
	v_add_f32_e32 v143, 1.0, v169
	v_rcp_f32_e32 v128, v128
	v_rcp_f32_e32 v129, v129
	v_rcp_f32_e32 v169, v143
	v_rcp_f32_e32 v143, v137
	v_pk_mul_f32 v[134:135], v[134:135], v[166:167]
	v_pk_mul_f32 v[132:133], v[132:133], v[128:129]
	v_pk_mul_f32 v[130:131], v[130:131], v[168:169]
	v_pk_mul_f32 v[140:141], v[140:141], v[142:143]
.LBB0_209:
	v_mov_b32_e32 v137, v136
	v_mov_b32_e32 v128, v136
	v_mov_b32_e32 v129, v136
	v_pk_mul_f32 v[134:135], v[128:129], v[134:135]
	v_pk_mul_f32 v[132:133], v[136:137], v[132:133]
	v_pk_mul_f32 v[142:143], v[128:129], v[130:131]
	v_cvt_pk_bf16_f32 v130, v132, v133
	v_cvt_pk_bf16_f32 v131, v134, v135
	v_pk_mul_f32 v[140:141], v[136:137], v[140:141]
	v_pk_add_f32 v[126:127], v[126:127], v[234:235]
	v_cvt_pk_bf16_f32 v132, v140, v141
	v_cvt_pk_bf16_f32 v133, v142, v143
	global_store_dwordx4 v138, v[130:133], s[8:9] offset:256 nt
	v_pk_add_f32 v[124:125], v[124:125], v[232:233]
	v_pk_add_f32 v[122:123], v[122:123], v[238:239]
	s_and_b64 vcc, exec, s[4:5]
	v_pk_add_f32 v[130:131], v[120:121], v[236:237]
	s_cbranch_vccnz .LBB0_211
	v_mul_f32_e32 v121, 0xbfb8aa3b, v130
	v_mul_f32_e32 v132, 0xbfb8aa3b, v125
	v_exp_f32_e32 v121, v121
	v_exp_f32_e32 v133, v132
	v_mul_f32_e32 v135, 0xbfb8aa3b, v122
	v_mul_f32_e32 v138, 0xbfb8aa3b, v127
	v_add_f32_e32 v121, 1.0, v121
	v_mul_f32_e32 v120, 0xbfb8aa3b, v124
	v_rcp_f32_e32 v132, v121
	v_add_f32_e32 v121, 1.0, v133
	v_mul_f32_e32 v133, 0xbfb8aa3b, v131
	v_mul_f32_e32 v134, 0xbfb8aa3b, v126
	v_exp_f32_e32 v135, v135
	v_exp_f32_e32 v139, v138
	v_mul_f32_e32 v138, 0xbfb8aa3b, v123
	v_exp_f32_e32 v120, v120
	v_exp_f32_e32 v133, v133
	v_exp_f32_e32 v134, v134
	v_exp_f32_e32 v140, v138
	v_add_f32_e32 v135, 1.0, v135
	v_add_f32_e32 v120, 1.0, v120
	v_add_f32_e32 v133, 1.0, v133
	v_add_f32_e32 v134, 1.0, v134
	v_rcp_f32_e32 v138, v135
	v_add_f32_e32 v135, 1.0, v139
	v_add_f32_e32 v139, 1.0, v140
	v_rcp_f32_e32 v120, v120
	v_rcp_f32_e32 v121, v121
	v_rcp_f32_e32 v134, v134
	v_rcp_f32_e32 v135, v135
	v_rcp_f32_e32 v139, v139
	v_rcp_f32_e32 v133, v133
	v_pk_mul_f32 v[124:125], v[124:125], v[120:121]
	v_pk_mul_f32 v[126:127], v[126:127], v[134:135]
	v_pk_mul_f32 v[122:123], v[122:123], v[138:139]
	v_pk_mul_f32 v[130:131], v[130:131], v[132:133]
.LBB0_211:
	v_add_u32_e32 v132, 16, v175
	v_mad_u32_u24 v120, v132, s71, v248
	v_pk_mul_f32 v[126:127], v[128:129], v[126:127]
	v_pk_mul_f32 v[124:125], v[136:137], v[124:125]
	v_pk_mul_f32 v[128:129], v[128:129], v[122:123]
	v_cvt_pk_bf16_f32 v122, v124, v125
	v_cvt_pk_bf16_f32 v123, v126, v127
	v_pk_mul_f32 v[130:131], v[136:137], v[130:131]
	v_pk_add_f32 v[118:119], v[118:119], v[246:247]
	v_cvt_pk_bf16_f32 v124, v130, v131
	v_cvt_pk_bf16_f32 v125, v128, v129
	global_store_dwordx4 v120, v[122:125], s[8:9] nt
	v_pk_add_f32 v[116:117], v[116:117], v[244:245]
	v_pk_add_f32 v[114:115], v[114:115], v[242:243]
	s_and_b64 vcc, exec, s[4:5]
	v_pk_add_f32 v[122:123], v[112:113], v[240:241]
	s_cbranch_vccnz .LBB0_213
	v_mul_f32_e32 v113, 0xbfb8aa3b, v122
	v_mul_f32_e32 v124, 0xbfb8aa3b, v117
	v_exp_f32_e32 v113, v113
	v_exp_f32_e32 v125, v124
	v_mul_f32_e32 v127, 0xbfb8aa3b, v114
	v_mul_f32_e32 v128, 0xbfb8aa3b, v119
	v_add_f32_e32 v113, 1.0, v113
	v_mul_f32_e32 v112, 0xbfb8aa3b, v116
	v_rcp_f32_e32 v124, v113
	v_add_f32_e32 v113, 1.0, v125
	v_mul_f32_e32 v125, 0xbfb8aa3b, v123
	v_mul_f32_e32 v126, 0xbfb8aa3b, v118
	v_exp_f32_e32 v127, v127
	v_exp_f32_e32 v129, v128
	v_mul_f32_e32 v128, 0xbfb8aa3b, v115
	v_exp_f32_e32 v112, v112
	v_exp_f32_e32 v125, v125
	v_exp_f32_e32 v126, v126
	v_exp_f32_e32 v130, v128
	v_add_f32_e32 v127, 1.0, v127
	v_add_f32_e32 v112, 1.0, v112
	v_add_f32_e32 v125, 1.0, v125
	v_add_f32_e32 v126, 1.0, v126
	v_rcp_f32_e32 v128, v127
	v_add_f32_e32 v127, 1.0, v129
	v_add_f32_e32 v129, 1.0, v130
	v_rcp_f32_e32 v112, v112
	v_rcp_f32_e32 v113, v113
	v_rcp_f32_e32 v126, v126
	v_rcp_f32_e32 v127, v127
	v_rcp_f32_e32 v129, v129
	v_rcp_f32_e32 v125, v125
	v_pk_mul_f32 v[116:117], v[116:117], v[112:113]
	v_pk_mul_f32 v[118:119], v[118:119], v[126:127]
	v_pk_mul_f32 v[114:115], v[114:115], v[128:129]
	v_pk_mul_f32 v[122:123], v[122:123], v[124:125]
.LBB0_213:
	v_mov_b32_e32 v112, v136
	v_mov_b32_e32 v113, v136
	v_pk_mul_f32 v[118:119], v[112:113], v[118:119]
	v_pk_mul_f32 v[116:117], v[136:137], v[116:117]
	v_pk_mul_f32 v[124:125], v[112:113], v[114:115]
	v_cvt_pk_bf16_f32 v114, v116, v117
	v_cvt_pk_bf16_f32 v115, v118, v119
	v_pk_mul_f32 v[122:123], v[136:137], v[122:123]
	v_pk_add_f32 v[110:111], v[110:111], v[234:235]
	v_cvt_pk_bf16_f32 v116, v122, v123
	v_cvt_pk_bf16_f32 v117, v124, v125
	global_store_dwordx4 v120, v[114:117], s[8:9] offset:256 nt
	v_pk_add_f32 v[108:109], v[108:109], v[232:233]
	v_pk_add_f32 v[106:107], v[106:107], v[238:239]
	s_and_b64 vcc, exec, s[4:5]
	v_pk_add_f32 v[114:115], v[104:105], v[236:237]
	s_cbranch_vccnz .LBB0_215
	v_mul_f32_e32 v105, 0xbfb8aa3b, v114
	v_mul_f32_e32 v116, 0xbfb8aa3b, v109
	v_exp_f32_e32 v105, v105
	v_exp_f32_e32 v117, v116
	v_mul_f32_e32 v119, 0xbfb8aa3b, v106
	v_mul_f32_e32 v120, 0xbfb8aa3b, v111
	v_add_f32_e32 v105, 1.0, v105
	v_mul_f32_e32 v104, 0xbfb8aa3b, v108
	v_rcp_f32_e32 v116, v105
	v_add_f32_e32 v105, 1.0, v117
	v_mul_f32_e32 v117, 0xbfb8aa3b, v115
	v_mul_f32_e32 v118, 0xbfb8aa3b, v110
	v_exp_f32_e32 v119, v119
	v_exp_f32_e32 v121, v120
	v_mul_f32_e32 v120, 0xbfb8aa3b, v107
	v_exp_f32_e32 v104, v104
	v_exp_f32_e32 v117, v117
	v_exp_f32_e32 v118, v118
	v_exp_f32_e32 v122, v120
	v_add_f32_e32 v119, 1.0, v119
	v_add_f32_e32 v104, 1.0, v104
	v_add_f32_e32 v117, 1.0, v117
	v_add_f32_e32 v118, 1.0, v118
	v_rcp_f32_e32 v120, v119
	v_add_f32_e32 v119, 1.0, v121
	v_add_f32_e32 v121, 1.0, v122
	v_rcp_f32_e32 v104, v104
	v_rcp_f32_e32 v105, v105
	v_rcp_f32_e32 v118, v118
	v_rcp_f32_e32 v119, v119
	v_rcp_f32_e32 v121, v121
	v_rcp_f32_e32 v117, v117
	v_pk_mul_f32 v[108:109], v[108:109], v[104:105]
	v_pk_mul_f32 v[110:111], v[110:111], v[118:119]
	v_pk_mul_f32 v[106:107], v[106:107], v[120:121]
	v_pk_mul_f32 v[114:115], v[114:115], v[116:117]
.LBB0_215:
	v_add_u32_e32 v116, 32, v175
	v_mad_u32_u24 v104, v116, s71, v248
	v_pk_mul_f32 v[110:111], v[112:113], v[110:111]
	v_pk_mul_f32 v[108:109], v[136:137], v[108:109]
	v_pk_mul_f32 v[112:113], v[112:113], v[106:107]
	v_cvt_pk_bf16_f32 v106, v108, v109
	v_cvt_pk_bf16_f32 v107, v110, v111
	v_pk_mul_f32 v[114:115], v[136:137], v[114:115]
	v_pk_add_f32 v[102:103], v[102:103], v[246:247]
	v_cvt_pk_bf16_f32 v108, v114, v115
	v_cvt_pk_bf16_f32 v109, v112, v113
	global_store_dwordx4 v104, v[106:109], s[8:9] nt
	v_pk_add_f32 v[100:101], v[100:101], v[244:245]
	v_pk_add_f32 v[98:99], v[98:99], v[242:243]
	s_and_b64 vcc, exec, s[4:5]
	v_pk_add_f32 v[106:107], v[96:97], v[240:241]
	s_cbranch_vccnz .LBB0_217
	v_mul_f32_e32 v97, 0xbfb8aa3b, v106
	v_mul_f32_e32 v108, 0xbfb8aa3b, v101
	v_exp_f32_e32 v97, v97
	v_exp_f32_e32 v109, v108
	v_mul_f32_e32 v111, 0xbfb8aa3b, v98
	v_mul_f32_e32 v112, 0xbfb8aa3b, v103
	v_add_f32_e32 v97, 1.0, v97
	v_mul_f32_e32 v96, 0xbfb8aa3b, v100
	v_rcp_f32_e32 v108, v97
	v_add_f32_e32 v97, 1.0, v109
	v_mul_f32_e32 v109, 0xbfb8aa3b, v107
	v_mul_f32_e32 v110, 0xbfb8aa3b, v102
	v_exp_f32_e32 v111, v111
	v_exp_f32_e32 v113, v112
	v_mul_f32_e32 v112, 0xbfb8aa3b, v99
	v_exp_f32_e32 v96, v96
	v_exp_f32_e32 v109, v109
	v_exp_f32_e32 v110, v110
	v_exp_f32_e32 v114, v112
	v_add_f32_e32 v111, 1.0, v111
	v_add_f32_e32 v96, 1.0, v96
	v_add_f32_e32 v109, 1.0, v109
	v_add_f32_e32 v110, 1.0, v110
	v_rcp_f32_e32 v112, v111
	v_add_f32_e32 v111, 1.0, v113
	v_add_f32_e32 v113, 1.0, v114
	v_rcp_f32_e32 v96, v96
	v_rcp_f32_e32 v97, v97
	v_rcp_f32_e32 v110, v110
	v_rcp_f32_e32 v111, v111
	v_rcp_f32_e32 v113, v113
	v_rcp_f32_e32 v109, v109
	v_pk_mul_f32 v[100:101], v[100:101], v[96:97]
	v_pk_mul_f32 v[102:103], v[102:103], v[110:111]
	v_pk_mul_f32 v[98:99], v[98:99], v[112:113]
	v_pk_mul_f32 v[106:107], v[106:107], v[108:109]
.LBB0_217:
	v_mov_b32_e32 v96, v136
	v_mov_b32_e32 v97, v136
	v_pk_mul_f32 v[102:103], v[96:97], v[102:103]
	v_pk_mul_f32 v[100:101], v[136:137], v[100:101]
	v_pk_mul_f32 v[108:109], v[96:97], v[98:99]
	v_cvt_pk_bf16_f32 v98, v100, v101
	v_cvt_pk_bf16_f32 v99, v102, v103
	v_pk_mul_f32 v[106:107], v[136:137], v[106:107]
	v_pk_add_f32 v[94:95], v[94:95], v[234:235]
	v_cvt_pk_bf16_f32 v100, v106, v107
	v_cvt_pk_bf16_f32 v101, v108, v109
	global_store_dwordx4 v104, v[98:101], s[8:9] offset:256 nt
	v_pk_add_f32 v[92:93], v[92:93], v[232:233]
	v_pk_add_f32 v[90:91], v[90:91], v[238:239]
	s_and_b64 vcc, exec, s[4:5]
	v_pk_add_f32 v[98:99], v[88:89], v[236:237]
	s_cbranch_vccnz .LBB0_219
	v_mul_f32_e32 v89, 0xbfb8aa3b, v98
	v_mul_f32_e32 v100, 0xbfb8aa3b, v93
	v_exp_f32_e32 v89, v89
	v_exp_f32_e32 v101, v100
	v_mul_f32_e32 v103, 0xbfb8aa3b, v90
	v_mul_f32_e32 v104, 0xbfb8aa3b, v95
	v_add_f32_e32 v89, 1.0, v89
	v_mul_f32_e32 v88, 0xbfb8aa3b, v92
	v_rcp_f32_e32 v100, v89
	v_add_f32_e32 v89, 1.0, v101
	v_mul_f32_e32 v101, 0xbfb8aa3b, v99
	v_mul_f32_e32 v102, 0xbfb8aa3b, v94
	v_exp_f32_e32 v103, v103
	v_exp_f32_e32 v105, v104
	v_mul_f32_e32 v104, 0xbfb8aa3b, v91
	v_exp_f32_e32 v88, v88
	v_exp_f32_e32 v101, v101
	v_exp_f32_e32 v102, v102
	v_exp_f32_e32 v106, v104
	v_add_f32_e32 v103, 1.0, v103
	v_add_f32_e32 v88, 1.0, v88
	v_add_f32_e32 v101, 1.0, v101
	v_add_f32_e32 v102, 1.0, v102
	v_rcp_f32_e32 v104, v103
	v_add_f32_e32 v103, 1.0, v105
	v_add_f32_e32 v105, 1.0, v106
	v_rcp_f32_e32 v88, v88
	v_rcp_f32_e32 v89, v89
	v_rcp_f32_e32 v102, v102
	v_rcp_f32_e32 v103, v103
	v_rcp_f32_e32 v105, v105
	v_rcp_f32_e32 v101, v101
	v_pk_mul_f32 v[92:93], v[92:93], v[88:89]
	v_pk_mul_f32 v[94:95], v[94:95], v[102:103]
	v_pk_mul_f32 v[90:91], v[90:91], v[104:105]
	v_pk_mul_f32 v[98:99], v[98:99], v[100:101]
.LBB0_219:
	v_add_u32_e32 v100, 48, v175
	v_mad_u32_u24 v88, v100, s71, v248
	v_pk_mul_f32 v[94:95], v[96:97], v[94:95]
	v_pk_mul_f32 v[92:93], v[136:137], v[92:93]
	v_pk_mul_f32 v[96:97], v[96:97], v[90:91]
	v_cvt_pk_bf16_f32 v90, v92, v93
	v_cvt_pk_bf16_f32 v91, v94, v95
	v_pk_mul_f32 v[98:99], v[136:137], v[98:99]
	v_pk_add_f32 v[86:87], v[86:87], v[246:247]
	v_cvt_pk_bf16_f32 v92, v98, v99
	v_cvt_pk_bf16_f32 v93, v96, v97
	global_store_dwordx4 v88, v[90:93], s[8:9] nt
	v_pk_add_f32 v[84:85], v[84:85], v[244:245]
	v_pk_add_f32 v[82:83], v[82:83], v[242:243]
	s_and_b64 vcc, exec, s[4:5]
	v_pk_add_f32 v[90:91], v[80:81], v[240:241]
	s_cbranch_vccnz .LBB0_221
	v_mul_f32_e32 v81, 0xbfb8aa3b, v90
	v_mul_f32_e32 v92, 0xbfb8aa3b, v85
	v_exp_f32_e32 v81, v81
	v_exp_f32_e32 v93, v92
	v_mul_f32_e32 v95, 0xbfb8aa3b, v82
	v_mul_f32_e32 v96, 0xbfb8aa3b, v87
	v_add_f32_e32 v81, 1.0, v81
	v_mul_f32_e32 v80, 0xbfb8aa3b, v84
	v_rcp_f32_e32 v92, v81
	v_add_f32_e32 v81, 1.0, v93
	v_mul_f32_e32 v93, 0xbfb8aa3b, v91
	v_mul_f32_e32 v94, 0xbfb8aa3b, v86
	v_exp_f32_e32 v95, v95
	v_exp_f32_e32 v97, v96
	v_mul_f32_e32 v96, 0xbfb8aa3b, v83
	v_exp_f32_e32 v80, v80
	v_exp_f32_e32 v93, v93
	v_exp_f32_e32 v94, v94
	v_exp_f32_e32 v98, v96
	v_add_f32_e32 v95, 1.0, v95
	v_add_f32_e32 v80, 1.0, v80
	v_add_f32_e32 v93, 1.0, v93
	v_add_f32_e32 v94, 1.0, v94
	v_rcp_f32_e32 v96, v95
	v_add_f32_e32 v95, 1.0, v97
	v_add_f32_e32 v97, 1.0, v98
	v_rcp_f32_e32 v80, v80
	v_rcp_f32_e32 v81, v81
	v_rcp_f32_e32 v94, v94
	v_rcp_f32_e32 v95, v95
	v_rcp_f32_e32 v97, v97
	v_rcp_f32_e32 v93, v93
	v_pk_mul_f32 v[84:85], v[84:85], v[80:81]
	v_pk_mul_f32 v[86:87], v[86:87], v[94:95]
	v_pk_mul_f32 v[82:83], v[82:83], v[96:97]
	v_pk_mul_f32 v[90:91], v[90:91], v[92:93]
.LBB0_221:
	v_mov_b32_e32 v80, v136
	v_mov_b32_e32 v81, v136
	v_pk_mul_f32 v[86:87], v[80:81], v[86:87]
	v_pk_mul_f32 v[84:85], v[136:137], v[84:85]
	v_pk_mul_f32 v[92:93], v[80:81], v[82:83]
	v_cvt_pk_bf16_f32 v82, v84, v85
	v_cvt_pk_bf16_f32 v83, v86, v87
	v_pk_mul_f32 v[90:91], v[136:137], v[90:91]
	v_pk_add_f32 v[78:79], v[78:79], v[234:235]
	v_cvt_pk_bf16_f32 v84, v90, v91
	v_cvt_pk_bf16_f32 v85, v92, v93
	global_store_dwordx4 v88, v[82:85], s[8:9] offset:256 nt
	v_pk_add_f32 v[76:77], v[76:77], v[232:233]
	v_pk_add_f32 v[70:71], v[70:71], v[238:239]
	s_and_b64 vcc, exec, s[4:5]
	v_pk_add_f32 v[82:83], v[68:69], v[236:237]
	s_cbranch_vccnz .LBB0_223
	v_mul_f32_e32 v69, 0xbfb8aa3b, v82
	v_mul_f32_e32 v84, 0xbfb8aa3b, v77
	v_exp_f32_e32 v69, v69
	v_exp_f32_e32 v85, v84
	v_mul_f32_e32 v87, 0xbfb8aa3b, v70
	v_mul_f32_e32 v88, 0xbfb8aa3b, v79
	v_add_f32_e32 v69, 1.0, v69
	v_mul_f32_e32 v68, 0xbfb8aa3b, v76
	v_rcp_f32_e32 v84, v69
	v_add_f32_e32 v69, 1.0, v85
	v_mul_f32_e32 v85, 0xbfb8aa3b, v83
	v_mul_f32_e32 v86, 0xbfb8aa3b, v78
	v_exp_f32_e32 v87, v87
	v_exp_f32_e32 v89, v88
	v_mul_f32_e32 v88, 0xbfb8aa3b, v71
	v_exp_f32_e32 v68, v68
	v_exp_f32_e32 v85, v85
	v_exp_f32_e32 v86, v86
	v_exp_f32_e32 v90, v88
	v_add_f32_e32 v87, 1.0, v87
	v_add_f32_e32 v68, 1.0, v68
	v_add_f32_e32 v85, 1.0, v85
	v_add_f32_e32 v86, 1.0, v86
	v_rcp_f32_e32 v88, v87
	v_add_f32_e32 v87, 1.0, v89
	v_add_f32_e32 v89, 1.0, v90
	v_rcp_f32_e32 v68, v68
	v_rcp_f32_e32 v69, v69
	v_rcp_f32_e32 v86, v86
	v_rcp_f32_e32 v87, v87
	v_rcp_f32_e32 v89, v89
	v_rcp_f32_e32 v85, v85
	v_pk_mul_f32 v[76:77], v[76:77], v[68:69]
	v_pk_mul_f32 v[78:79], v[78:79], v[86:87]
	v_pk_mul_f32 v[70:71], v[70:71], v[88:89]
	v_pk_mul_f32 v[82:83], v[82:83], v[84:85]
.LBB0_223:
	v_add_u32_e32 v84, 0x80, v175
	v_pk_mul_f32 v[78:79], v[80:81], v[78:79]
	v_pk_mul_f32 v[76:77], v[136:137], v[76:77]
	v_pk_mul_f32 v[70:71], v[80:81], v[70:71]
	v_mad_u32_u24 v68, v84, s71, v248
	v_pk_mul_f32 v[80:81], v[136:137], v[82:83]
	v_cvt_pk_bf16_f32 v76, v76, v77
	v_cvt_pk_bf16_f32 v77, v78, v79
	v_pk_add_f32 v[58:59], v[58:59], v[246:247]
	v_cvt_pk_bf16_f32 v78, v80, v81
	v_cvt_pk_bf16_f32 v79, v70, v71
	v_pk_add_f32 v[56:57], v[56:57], v[244:245]
	v_pk_add_f32 v[50:51], v[50:51], v[242:243]
	s_and_b64 vcc, exec, s[4:5]
	v_pk_add_f32 v[70:71], v[48:49], v[240:241]
	global_store_dwordx4 v68, v[76:79], s[8:9] nt
	s_cbranch_vccnz .LBB0_225
	v_mul_f32_e32 v49, 0xbfb8aa3b, v70
	v_mul_f32_e32 v76, 0xbfb8aa3b, v57
	v_exp_f32_e32 v49, v49
	v_exp_f32_e32 v77, v76
	v_mul_f32_e32 v79, 0xbfb8aa3b, v50
	v_mul_f32_e32 v80, 0xbfb8aa3b, v59
	v_add_f32_e32 v49, 1.0, v49
	v_mul_f32_e32 v48, 0xbfb8aa3b, v56
	v_rcp_f32_e32 v76, v49
	v_add_f32_e32 v49, 1.0, v77
	v_mul_f32_e32 v77, 0xbfb8aa3b, v71
	v_mul_f32_e32 v78, 0xbfb8aa3b, v58
	v_exp_f32_e32 v79, v79
	v_exp_f32_e32 v81, v80
	v_mul_f32_e32 v80, 0xbfb8aa3b, v51
	v_exp_f32_e32 v48, v48
	v_exp_f32_e32 v77, v77
	v_exp_f32_e32 v78, v78
	v_exp_f32_e32 v82, v80
	v_add_f32_e32 v79, 1.0, v79
	v_add_f32_e32 v48, 1.0, v48
	v_add_f32_e32 v77, 1.0, v77
	v_add_f32_e32 v78, 1.0, v78
	v_rcp_f32_e32 v80, v79
	v_add_f32_e32 v79, 1.0, v81
	v_add_f32_e32 v81, 1.0, v82
	v_rcp_f32_e32 v48, v48
	v_rcp_f32_e32 v49, v49
	v_rcp_f32_e32 v78, v78
	v_rcp_f32_e32 v79, v79
	v_rcp_f32_e32 v81, v81
	v_rcp_f32_e32 v77, v77
	v_pk_mul_f32 v[56:57], v[56:57], v[48:49]
	v_pk_mul_f32 v[58:59], v[58:59], v[78:79]
	v_pk_mul_f32 v[50:51], v[50:51], v[80:81]
	v_pk_mul_f32 v[70:71], v[70:71], v[76:77]
.LBB0_225:
	v_mov_b32_e32 v48, v136
	v_mov_b32_e32 v49, v136
	v_pk_mul_f32 v[58:59], v[48:49], v[58:59]
	v_pk_mul_f32 v[56:57], v[136:137], v[56:57]
	v_pk_mul_f32 v[50:51], v[48:49], v[50:51]
	v_pk_mul_f32 v[70:71], v[136:137], v[70:71]
	v_cvt_pk_bf16_f32 v56, v56, v57
	v_cvt_pk_bf16_f32 v57, v58, v59
	v_pk_add_f32 v[46:47], v[46:47], v[234:235]
	v_cvt_pk_bf16_f32 v58, v70, v71
	v_cvt_pk_bf16_f32 v59, v50, v51
	v_pk_add_f32 v[44:45], v[44:45], v[232:233]
	v_pk_add_f32 v[42:43], v[42:43], v[238:239]
	s_and_b64 vcc, exec, s[4:5]
	v_pk_add_f32 v[50:51], v[40:41], v[236:237]
	global_store_dwordx4 v68, v[56:59], s[8:9] offset:256 nt
	s_cbranch_vccnz .LBB0_227
	v_mul_f32_e32 v41, 0xbfb8aa3b, v50
	v_mul_f32_e32 v56, 0xbfb8aa3b, v45
	v_exp_f32_e32 v41, v41
	v_exp_f32_e32 v57, v56
	v_mul_f32_e32 v59, 0xbfb8aa3b, v42
	v_mul_f32_e32 v68, 0xbfb8aa3b, v47
	v_add_f32_e32 v41, 1.0, v41
	v_mul_f32_e32 v40, 0xbfb8aa3b, v44
	v_rcp_f32_e32 v56, v41
	v_add_f32_e32 v41, 1.0, v57
	v_mul_f32_e32 v57, 0xbfb8aa3b, v51
	v_mul_f32_e32 v58, 0xbfb8aa3b, v46
	v_exp_f32_e32 v59, v59
	v_exp_f32_e32 v69, v68
	v_mul_f32_e32 v68, 0xbfb8aa3b, v43
	v_exp_f32_e32 v40, v40
	v_exp_f32_e32 v57, v57
	v_exp_f32_e32 v58, v58
	v_exp_f32_e32 v70, v68
	v_add_f32_e32 v59, 1.0, v59
	v_add_f32_e32 v40, 1.0, v40
	v_add_f32_e32 v57, 1.0, v57
	v_add_f32_e32 v58, 1.0, v58
	v_rcp_f32_e32 v68, v59
	v_add_f32_e32 v59, 1.0, v69
	v_add_f32_e32 v69, 1.0, v70
	v_rcp_f32_e32 v40, v40
	v_rcp_f32_e32 v41, v41
	v_rcp_f32_e32 v58, v58
	v_rcp_f32_e32 v59, v59
	v_rcp_f32_e32 v69, v69
	v_rcp_f32_e32 v57, v57
	v_pk_mul_f32 v[44:45], v[44:45], v[40:41]
	v_pk_mul_f32 v[46:47], v[46:47], v[58:59]
	v_pk_mul_f32 v[42:43], v[42:43], v[68:69]
	v_pk_mul_f32 v[50:51], v[50:51], v[56:57]
.LBB0_227:
	s_nop 0
	v_add_u32_e32 v56, 0x90, v175
	v_mad_u32_u24 v40, v56, s71, v248
	v_pk_mul_f32 v[46:47], v[48:49], v[46:47]
	v_pk_mul_f32 v[44:45], v[136:137], v[44:45]
	v_pk_mul_f32 v[48:49], v[48:49], v[42:43]
	v_cvt_pk_bf16_f32 v42, v44, v45
	v_cvt_pk_bf16_f32 v43, v46, v47
	v_pk_mul_f32 v[50:51], v[136:137], v[50:51]
	v_pk_add_f32 v[38:39], v[38:39], v[246:247]
	v_cvt_pk_bf16_f32 v44, v50, v51
	v_cvt_pk_bf16_f32 v45, v48, v49
	global_store_dwordx4 v40, v[42:45], s[8:9] nt
	v_pk_add_f32 v[36:37], v[36:37], v[244:245]
	v_pk_add_f32 v[34:35], v[34:35], v[242:243]
	s_and_b64 vcc, exec, s[4:5]
	v_pk_add_f32 v[42:43], v[32:33], v[240:241]
	s_cbranch_vccnz .LBB0_229
	v_mul_f32_e32 v33, 0xbfb8aa3b, v42
	v_mul_f32_e32 v44, 0xbfb8aa3b, v37
	v_exp_f32_e32 v33, v33
	v_exp_f32_e32 v45, v44
	v_mul_f32_e32 v47, 0xbfb8aa3b, v34
	v_mul_f32_e32 v48, 0xbfb8aa3b, v39
	v_add_f32_e32 v33, 1.0, v33
	v_mul_f32_e32 v32, 0xbfb8aa3b, v36
	v_rcp_f32_e32 v44, v33
	v_add_f32_e32 v33, 1.0, v45
	v_mul_f32_e32 v45, 0xbfb8aa3b, v43
	v_mul_f32_e32 v46, 0xbfb8aa3b, v38
	v_exp_f32_e32 v47, v47
	v_exp_f32_e32 v49, v48
	v_mul_f32_e32 v48, 0xbfb8aa3b, v35
	v_exp_f32_e32 v32, v32
	v_exp_f32_e32 v45, v45
	v_exp_f32_e32 v46, v46
	v_exp_f32_e32 v50, v48
	v_add_f32_e32 v47, 1.0, v47
	v_add_f32_e32 v32, 1.0, v32
	v_add_f32_e32 v45, 1.0, v45
	v_add_f32_e32 v46, 1.0, v46
	v_rcp_f32_e32 v48, v47
	v_add_f32_e32 v47, 1.0, v49
	v_add_f32_e32 v49, 1.0, v50
	v_rcp_f32_e32 v32, v32
	v_rcp_f32_e32 v33, v33
	v_rcp_f32_e32 v46, v46
	v_rcp_f32_e32 v47, v47
	v_rcp_f32_e32 v49, v49
	v_rcp_f32_e32 v45, v45
	v_pk_mul_f32 v[36:37], v[36:37], v[32:33]
	v_pk_mul_f32 v[38:39], v[38:39], v[46:47]
	v_pk_mul_f32 v[34:35], v[34:35], v[48:49]
	v_pk_mul_f32 v[42:43], v[42:43], v[44:45]
.LBB0_229:
	v_mov_b32_e32 v32, v136
	v_mov_b32_e32 v33, v136
	v_pk_mul_f32 v[38:39], v[32:33], v[38:39]
	v_pk_mul_f32 v[36:37], v[136:137], v[36:37]
	v_pk_mul_f32 v[44:45], v[32:33], v[34:35]
	v_cvt_pk_bf16_f32 v34, v36, v37
	v_cvt_pk_bf16_f32 v35, v38, v39
	v_pk_mul_f32 v[42:43], v[136:137], v[42:43]
	v_pk_add_f32 v[30:31], v[30:31], v[234:235]
	v_cvt_pk_bf16_f32 v36, v42, v43
	v_cvt_pk_bf16_f32 v37, v44, v45
	global_store_dwordx4 v40, v[34:37], s[8:9] offset:256 nt
	v_pk_add_f32 v[28:29], v[28:29], v[232:233]
	v_pk_add_f32 v[26:27], v[26:27], v[238:239]
	s_and_b64 vcc, exec, s[4:5]
	v_pk_add_f32 v[34:35], v[24:25], v[236:237]
	s_cbranch_vccnz .LBB0_231
	v_mul_f32_e32 v25, 0xbfb8aa3b, v34
	v_mul_f32_e32 v36, 0xbfb8aa3b, v29
	v_exp_f32_e32 v25, v25
	v_exp_f32_e32 v37, v36
	v_mul_f32_e32 v39, 0xbfb8aa3b, v26
	v_mul_f32_e32 v40, 0xbfb8aa3b, v31
	v_add_f32_e32 v25, 1.0, v25
	v_mul_f32_e32 v24, 0xbfb8aa3b, v28
	v_rcp_f32_e32 v36, v25
	v_add_f32_e32 v25, 1.0, v37
	v_mul_f32_e32 v37, 0xbfb8aa3b, v35
	v_mul_f32_e32 v38, 0xbfb8aa3b, v30
	v_exp_f32_e32 v39, v39
	v_exp_f32_e32 v41, v40
	v_mul_f32_e32 v40, 0xbfb8aa3b, v27
	v_exp_f32_e32 v24, v24
	v_exp_f32_e32 v37, v37
	v_exp_f32_e32 v38, v38
	v_exp_f32_e32 v42, v40
	v_add_f32_e32 v39, 1.0, v39
	v_add_f32_e32 v24, 1.0, v24
	v_add_f32_e32 v37, 1.0, v37
	v_add_f32_e32 v38, 1.0, v38
	v_rcp_f32_e32 v40, v39
	v_add_f32_e32 v39, 1.0, v41
	v_add_f32_e32 v41, 1.0, v42
	v_rcp_f32_e32 v24, v24
	v_rcp_f32_e32 v25, v25
	v_rcp_f32_e32 v38, v38
	v_rcp_f32_e32 v39, v39
	v_rcp_f32_e32 v41, v41
	v_rcp_f32_e32 v37, v37
	v_pk_mul_f32 v[28:29], v[28:29], v[24:25]
	v_pk_mul_f32 v[30:31], v[30:31], v[38:39]
	v_pk_mul_f32 v[26:27], v[26:27], v[40:41]
	v_pk_mul_f32 v[34:35], v[34:35], v[36:37]
.LBB0_231:
	v_add_u32_e32 v36, 0xa0, v175
	v_mad_u32_u24 v24, v36, s71, v248
	v_pk_mul_f32 v[30:31], v[32:33], v[30:31]
	v_pk_mul_f32 v[28:29], v[136:137], v[28:29]
	v_pk_mul_f32 v[32:33], v[32:33], v[26:27]
	v_cvt_pk_bf16_f32 v26, v28, v29
	v_cvt_pk_bf16_f32 v27, v30, v31
	v_pk_mul_f32 v[34:35], v[136:137], v[34:35]
	v_pk_add_f32 v[22:23], v[22:23], v[246:247]
	v_cvt_pk_bf16_f32 v28, v34, v35
	v_cvt_pk_bf16_f32 v29, v32, v33
	global_store_dwordx4 v24, v[26:29], s[8:9] nt
	v_pk_add_f32 v[20:21], v[20:21], v[244:245]
	v_pk_add_f32 v[18:19], v[18:19], v[242:243]
	s_and_b64 vcc, exec, s[4:5]
	v_pk_add_f32 v[26:27], v[16:17], v[240:241]
	s_cbranch_vccnz .LBB0_233
	v_mul_f32_e32 v17, 0xbfb8aa3b, v26
	v_mul_f32_e32 v28, 0xbfb8aa3b, v21
	v_exp_f32_e32 v17, v17
	v_exp_f32_e32 v29, v28
	v_mul_f32_e32 v31, 0xbfb8aa3b, v18
	v_mul_f32_e32 v32, 0xbfb8aa3b, v23
	v_add_f32_e32 v17, 1.0, v17
	v_mul_f32_e32 v16, 0xbfb8aa3b, v20
	v_rcp_f32_e32 v28, v17
	v_add_f32_e32 v17, 1.0, v29
	v_mul_f32_e32 v29, 0xbfb8aa3b, v27
	v_mul_f32_e32 v30, 0xbfb8aa3b, v22
	v_exp_f32_e32 v31, v31
	v_exp_f32_e32 v33, v32
	v_mul_f32_e32 v32, 0xbfb8aa3b, v19
	v_exp_f32_e32 v16, v16
	v_exp_f32_e32 v29, v29
	v_exp_f32_e32 v30, v30
	v_exp_f32_e32 v34, v32
	v_add_f32_e32 v31, 1.0, v31
	v_add_f32_e32 v16, 1.0, v16
	v_add_f32_e32 v29, 1.0, v29
	v_add_f32_e32 v30, 1.0, v30
	v_rcp_f32_e32 v32, v31
	v_add_f32_e32 v31, 1.0, v33
	v_add_f32_e32 v33, 1.0, v34
	v_rcp_f32_e32 v16, v16
	v_rcp_f32_e32 v17, v17
	v_rcp_f32_e32 v30, v30
	v_rcp_f32_e32 v31, v31
	v_rcp_f32_e32 v33, v33
	v_rcp_f32_e32 v29, v29
	v_pk_mul_f32 v[20:21], v[20:21], v[16:17]
	v_pk_mul_f32 v[22:23], v[22:23], v[30:31]
	v_pk_mul_f32 v[18:19], v[18:19], v[32:33]
	v_pk_mul_f32 v[26:27], v[26:27], v[28:29]
.LBB0_233:
	v_mov_b32_e32 v16, v136
	v_mov_b32_e32 v17, v136
	v_pk_mul_f32 v[22:23], v[16:17], v[22:23]
	v_pk_mul_f32 v[20:21], v[136:137], v[20:21]
	v_pk_mul_f32 v[28:29], v[16:17], v[18:19]
	v_cvt_pk_bf16_f32 v18, v20, v21
	v_cvt_pk_bf16_f32 v19, v22, v23
	v_pk_mul_f32 v[26:27], v[136:137], v[26:27]
	v_pk_add_f32 v[14:15], v[14:15], v[234:235]
	v_cvt_pk_bf16_f32 v20, v26, v27
	v_cvt_pk_bf16_f32 v21, v28, v29
	global_store_dwordx4 v24, v[18:21], s[8:9] offset:256 nt
	v_pk_add_f32 v[12:13], v[12:13], v[232:233]
	v_pk_add_f32 v[10:11], v[10:11], v[238:239]
	s_and_b64 vcc, exec, s[4:5]
	v_pk_add_f32 v[18:19], v[8:9], v[236:237]
	s_cbranch_vccnz .LBB0_235
	v_mul_f32_e32 v9, 0xbfb8aa3b, v18
	v_mul_f32_e32 v20, 0xbfb8aa3b, v13
	v_exp_f32_e32 v9, v9
	v_exp_f32_e32 v21, v20
	v_mul_f32_e32 v23, 0xbfb8aa3b, v10
	v_mul_f32_e32 v24, 0xbfb8aa3b, v15
	v_add_f32_e32 v9, 1.0, v9
	v_mul_f32_e32 v8, 0xbfb8aa3b, v12
	v_rcp_f32_e32 v20, v9
	v_add_f32_e32 v9, 1.0, v21
	v_mul_f32_e32 v21, 0xbfb8aa3b, v19
	v_mul_f32_e32 v22, 0xbfb8aa3b, v14
	v_exp_f32_e32 v23, v23
	v_exp_f32_e32 v25, v24
	v_mul_f32_e32 v24, 0xbfb8aa3b, v11
	v_exp_f32_e32 v8, v8
	v_exp_f32_e32 v21, v21
	v_exp_f32_e32 v22, v22
	v_exp_f32_e32 v26, v24
	v_add_f32_e32 v23, 1.0, v23
	v_add_f32_e32 v8, 1.0, v8
	v_add_f32_e32 v21, 1.0, v21
	v_add_f32_e32 v22, 1.0, v22
	v_rcp_f32_e32 v24, v23
	v_add_f32_e32 v23, 1.0, v25
	v_add_f32_e32 v25, 1.0, v26
	v_rcp_f32_e32 v8, v8
	v_rcp_f32_e32 v9, v9
	v_rcp_f32_e32 v22, v22
	v_rcp_f32_e32 v23, v23
	v_rcp_f32_e32 v25, v25
	v_rcp_f32_e32 v21, v21
	v_pk_mul_f32 v[12:13], v[12:13], v[8:9]
	v_pk_mul_f32 v[14:15], v[14:15], v[22:23]
	v_pk_mul_f32 v[10:11], v[10:11], v[24:25]
	v_pk_mul_f32 v[18:19], v[18:19], v[20:21]
.LBB0_235:
	v_add_u32_e32 v20, 0xb0, v175
	v_mad_u32_u24 v8, v20, s71, v248
	v_pk_mul_f32 v[12:13], v[136:137], v[12:13]
	v_pk_add_f32 v[6:7], v[6:7], v[246:247]
	v_pk_add_f32 v[4:5], v[4:5], v[244:245]
	v_pk_add_f32 v[2:3], v[2:3], v[242:243]
	s_and_b64 vcc, exec, s[4:5]
	v_pk_add_f32 v[0:1], v[0:1], v[240:241]
	v_pk_mul_f32 v[14:15], v[16:17], v[14:15]
	v_pk_mul_f32 v[16:17], v[16:17], v[10:11]
	v_pk_mul_f32 v[18:19], v[136:137], v[18:19]
	v_cvt_pk_bf16_f32 v10, v12, v13
	v_cvt_pk_bf16_f32 v11, v14, v15
	s_nop 0
	v_cvt_pk_bf16_f32 v12, v18, v19
	v_cvt_pk_bf16_f32 v13, v16, v17
	global_store_dwordx4 v8, v[10:13], s[8:9] nt
	s_cbranch_vccnz .LBB0_237
	s_nop 0
	v_mul_f32_e32 v11, 0xbfb8aa3b, v0
	v_mul_f32_e32 v12, 0xbfb8aa3b, v5
	v_exp_f32_e32 v11, v11
	v_exp_f32_e32 v13, v12
	v_mul_f32_e32 v15, 0xbfb8aa3b, v2
	v_mul_f32_e32 v16, 0xbfb8aa3b, v7
	v_add_f32_e32 v11, 1.0, v11
	v_mul_f32_e32 v10, 0xbfb8aa3b, v4
	v_rcp_f32_e32 v12, v11
	v_add_f32_e32 v11, 1.0, v13
	v_mul_f32_e32 v13, 0xbfb8aa3b, v1
	v_mul_f32_e32 v14, 0xbfb8aa3b, v6
	v_exp_f32_e32 v15, v15
	v_exp_f32_e32 v17, v16
	v_mul_f32_e32 v16, 0xbfb8aa3b, v3
	v_exp_f32_e32 v10, v10
	v_exp_f32_e32 v13, v13
	v_exp_f32_e32 v14, v14
	v_exp_f32_e32 v18, v16
	v_add_f32_e32 v15, 1.0, v15
	v_add_f32_e32 v10, 1.0, v10
	v_add_f32_e32 v13, 1.0, v13
	v_add_f32_e32 v14, 1.0, v14
	v_rcp_f32_e32 v16, v15
	v_add_f32_e32 v15, 1.0, v17
	v_add_f32_e32 v17, 1.0, v18
	v_rcp_f32_e32 v10, v10
	v_rcp_f32_e32 v11, v11
	v_rcp_f32_e32 v14, v14
	v_rcp_f32_e32 v15, v15
	v_rcp_f32_e32 v17, v17
	v_rcp_f32_e32 v13, v13
	v_pk_mul_f32 v[4:5], v[4:5], v[10:11]
	v_pk_mul_f32 v[6:7], v[6:7], v[14:15]
	v_pk_mul_f32 v[2:3], v[2:3], v[16:17]
	v_pk_mul_f32 v[0:1], v[0:1], v[12:13]

.LBB0_522:
	s_nop 0
	s_nop 0
	s_nop 0
	s_nop 0
	s_nop 0
	s_nop 0
	s_nop 0
	s_nop 0
	s_nop 0
	s_nop 0
	s_cmp_lt_i32 s80, 7
	s_cselect_b64 s[0:1], -1, 0
	s_cmp_gt_i32 s81, 6
	s_cselect_b64 s[4:5], -1, 0
	s_and_b64 s[0:1], s[0:1], s[4:5]
	s_andn2_b64 vcc, exec, s[0:1]
	s_cbranch_vccnz .LBB0_622
	v_lshrrev_b32_e32 v2, 1, v144
	v_lshrrev_b32_e32 v3, 5, v144
	v_and_b32_e32 v2, 24, v2
	v_and_b32_e32 v3, 4, v3
	v_bfe_u32 v4, v144, 2, 2
	v_lshlrev_b32_e32 v0, 4, v144
	v_and_b32_e32 v1, 32, v144
	v_bfe_u32 v10, v144, 2, 4
	v_or3_b32 v2, v3, v4, v2
	v_lshrrev_b32_e32 v3, 3, v144
	s_movk_i32 s0, 0x70
	v_bitop3_b32 v8, v0, v1, 48 bitop3:0x6c
	v_and_b32_e32 v9, 64, v144
	v_and_or_b32 v4, v3, s0, v10
	s_movk_i32 s0, 0x60
	v_add_u32_e32 v11, 0x2000, v0
	v_or_b32_e32 v1, v8, v9
	v_and_or_b32 v3, v3, s0, v2
	v_lshrrev_b32_e32 v0, 7, v11
	s_movk_i32 s0, 0xf0
	s_add_u32 s30, s62, 0x4000000
	v_lshl_or_b32 v150, v4, 12, v1
	v_and_or_b32 v3, v0, s0, v10
	s_movk_i32 s0, 0xe0
	s_addc_u32 s31, s63, 0
	v_and_or_b32 v0, v0, s0, v2
	s_lshl_b32 s0, s2, 2
	s_and_b32 s0, s0, 28
	s_ashr_i32 s1, s2, 6
	s_add_i32 s0, s0, s1
	s_waitcnt lgkmcnt(0)
	s_bfe_u32 s16, s2, 0x30003
	s_ashr_i32 s1, s0, 31
	s_lshl_b64 s[6:7], s[0:1], 20
	s_lshl_b32 s2, s16, 20
	s_add_u32 s1, s62, s2
	s_addc_u32 s3, s63, 0
	s_add_u32 s4, s1, 0x1200000
	s_addc_u32 s5, s3, 0
	s_add_u32 s8, s1, 0x1280000
	s_addc_u32 s9, s3, 0
	s_add_u32 s6, s30, s6
	s_addc_u32 s7, s31, s7
	s_add_u32 s10, s6, 0x80000
	v_readfirstlane_b32 s3, v144
	s_addc_u32 s11, s7, 0
	s_lshr_b32 s18, s3, 6
	s_lshl_b32 s1, s18, 10
	s_add_i32 s34, s1, 0
	s_add_i32 m0, s34, 0x10000
	v_lshl_or_b32 v154, v3, 12, v1
	global_load_lds_dwordx4 v150, s[4:5]
	s_add_i32 m0, s34, 0x12000
	v_lshl_or_b32 v148, v4, 12, v1
	global_load_lds_dwordx4 v154, s[4:5]
	s_add_i32 m0, s34, 0x14000
	s_add_i32 s35, s34, 0x2000
	global_load_lds_dwordx4 v150, s[8:9]
	s_add_i32 m0, s34, 0x16000
	v_lshl_or_b32 v152, v3, 12, v1
	global_load_lds_dwordx4 v154, s[8:9]
	s_mov_b32 m0, s34
	s_add_i32 s36, s34, 0x4000
	global_load_lds_dwordx4 v148, s[6:7]
	s_mov_b32 m0, s35
	s_add_i32 s37, s34, 0x6000
	global_load_lds_dwordx4 v152, s[6:7]
	s_mov_b32 m0, s36
	v_mov_b32_e32 v151, 0
	global_load_lds_dwordx4 v148, s[10:11]
	s_mov_b32 m0, s37
	s_lshr_b32 s19, s3, 8
	global_load_lds_dwordx4 v152, s[10:11]
	v_mov_b32_e32 v155, v151
	v_mov_b32_e32 v149, v151
	v_mov_b32_e32 v153, v151
	s_cmp_eq_u32 s19, 1
	s_mov_b32 s38, 0
	v_lshl_add_u64 v[0:1], s[4:5], 0, v[150:151]
	v_lshl_add_u64 v[2:3], s[4:5], 0, v[154:155]
	v_lshl_add_u64 v[4:5], s[6:7], 0, v[148:149]
	s_cselect_b64 s[8:9], -1, 0
	s_cmp_lg_u32 s19, 1
	v_lshl_add_u64 v[6:7], s[6:7], 0, v[152:153]
	s_cbranch_scc1 .LBB0_525
	s_barrier
